# one static priority raise for the younger wave half (waves 4-7) over the merged 4-phase projection GEMM loop
# speedup vs baseline: 1.0033x; 1.0033x over previous
;     DI bool next(int i, Unit& u) const {
;         const long L = (long)i * G + c; if (L >= nwg) return false;
;         int wgid = (int)L; { const int q = nwg / NXCD, r = nwg % NXCD, xcd = wgid % NXCD, off = wgid / NXCD; wgid = (xcd < r ? xcd * (q + 1) : r * (q + 1) + (xcd - r) * q) + off; }
;         const int nig = WGM * nN, gid = wgid / nig, fm = gid * WGM, gsz = (nM - fm) < WGM ? (nM - fm) : WGM;
;         u.pm = fm + ((wgid % nig) % gsz); u.pn = (wgid % nig) / gsz; return true;
; template <class Epi>
; DI void gemm_phase(LAS unsigned char* lds, const Gemm g, const StaticOrder& S, const Epi& E) {
;     ...
;     for (int i = 0; i < 2; ++i) { int R, C; stage_rc(tid * 16 + i * 8192, R, C); const int Rb = Epi::PERM ? ((R & ~31) + perm32(R & 31)) : R;
;         voffA[i] = (unsigned)(R * g.lda + C) * 2u; voffB[i] = (unsigned)(Rb * g.ldb + C) * 2u; }
;     const size_t kstep = (size_t)(BK * 2);
;     const size_t hstepA = (size_t)HALF * g.lda * 2, hstepB = (size_t)HALF * g.ldb * 2;
;     const size_t tstepA = 2 * hstepA, tstepB = 2 * hstepB;
;     const unsigned ldsw = (unsigned)wid * 1024u;
;     const int aoff = lds_byte(wr * 64 + fr, fq * 8), boff = lds_byte(wc * 32 + fr, fq * 8);
;     ...
;     Unit cur, nxt; int ui = 0;
;     if (!S.next(0, cur)) return;
;     f32x4 acc[2][2][4][2];
; #pragma unroll
;     for (int a = 0; a < 2; ++a)
; #pragma unroll
;         for (int b = 0; b < 2; ++b)
; #pragma unroll
;             for (int m = 0; m < 4; ++m)
; #pragma unroll
;                 for (int n = 0; n < 2; ++n) acc[a][b][m][n] = (f32x4){0.f, 0.f, 0.f, 0.f};
;     bf16x8 At[4][2], B0[2][2], B1[2][2];
;     const char* cA = (const char*)g.A + (size_t)cur.pm * tstepA; const char* cB = (const char*)g.Bt + (size_t)cur.pn * tstepB;
;     PG8_STAGE(PG8_SB(0, 0), cB, voffB); PG8_STAGE(PG8_SA(0, 0), cA, voffA); PG8_STAGE(PG8_SB(0, 1), cB + hstepB, voffB); PG8_STAGE(PG8_SA(0, 1), cA + hstepA, voffA);
;     if (wr == 1) PG8_BAR;
;     PG8_WAIT_V(4); PG8_BAR;
;     PG8_STAGE(PG8_SB(1, 0), cB + kstep, voffB); PG8_STAGE(PG8_SA(1, 0), cA + kstep, voffA); PG8_STAGE(PG8_SB(1, 1), cB + hstepB + kstep, voffB);
;     PG8_WAIT_V(6); PG8_BAR;
;     for (;;) {
;         const bool has_next = S.next(ui + 1, nxt);
;         const char* nA = has_next ? (const char*)g.A + (size_t)nxt.pm * tstepA : cA; const char* nB = has_next ? (const char*)g.Bt + (size_t)nxt.pn * tstepB : cB;
.LBB0_109:
	s_lshl_b32 s0, s4, 5
	s_mov_b64 s[4:5], 0x80
	s_and_b32 s17, s0, 0x60
	s_add_i32 m0, s9, 0x18000
	v_lshl_add_u64 v[6:7], v[6:7], 0, s[4:5]
	s_lshl_b32 s16, s3, 13
	s_lshl_b32 s46, s17, 7
	s_waitcnt vmcnt(2)
	s_barrier
	global_load_lds_dwordx4 v[6:7], off
	v_lshl_add_u64 v[4:5], v[4:5], 0, s[4:5]
	s_add_i32 m0, s9, 0x1a000
	s_add_i32 s71, s9, 0x8000
	s_add_i32 s72, s9, 0xa000
	global_load_lds_dwordx4 v[4:5], off
	v_lshl_add_u64 v[2:3], v[2:3], 0, s[4:5]
	s_mov_b32 m0, s71
	s_add_u32 s0, s54, 0x80080
	global_load_lds_dwordx4 v[2:3], off
	v_lshl_add_u64 v[0:1], v[0:1], 0, s[4:5]
	s_mov_b32 m0, s72
	s_addc_u32 s1, s55, 0
	global_load_lds_dwordx4 v[0:1], off
	s_add_i32 m0, s9, 0x1c000
	v_lshl_add_u64 v[0:1], s[0:1], 0, v[132:133]
	global_load_lds_dwordx4 v[0:1], off
	v_lshl_add_u64 v[0:1], s[0:1], 0, v[128:129]
	s_add_i32 m0, s9, 0x1e000
	s_add_i32 s75, 0, 0x10000
	global_load_lds_dwordx4 v[0:1], off
	v_lshrrev_b32_e32 v1, 1, v9
	v_and_b32_e32 v1, 24, v1
	v_and_b32_e32 v0, 15, v9
	v_lshlrev_b32_e32 v2, 1, v1
	v_lshl_or_b32 v144, s3, 6, v0
	v_lshl_or_b32 v0, v0, 6, v2
	v_lshlrev_b32_e32 v2, 2, v9
	v_and_b32_e32 v2, 32, v2
	v_bitop3_b32 v3, v0, s16, v2 bitop3:0xde
	v_bitop3_b32 v145, v0, s46, v2 bitop3:0xde
	v_lshlrev_b32_e32 v0, 15, v13
	v_and_b32_e32 v0, 0xffff0000, v0
	v_or_b32_e32 v146, s17, v1
	v_lshl_add_u32 v0, v12, 12, v0
	v_and_b32_e32 v1, 1, v13
	v_lshl_or_b32 v0, v1, 6, v0
	v_lshl_add_u32 v136, v14, 1, v0
	v_lshlrev_b32_e32 v0, 15, v8
	v_and_b32_e32 v0, 0xffff0000, v0
	s_waitcnt vmcnt(6)
	v_lshl_add_u32 v0, v10, 12, v0
	v_and_b32_e32 v1, 1, v8
	v_lshl_or_b32 v0, v1, 6, v0
	s_add_i32 s76, 0, 0x14000
	s_sext_i32_i16 s78, s2
	s_ashr_i32 s73, s10, 31
	s_mov_b32 s74, s10
	v_mov_b32_e32 v137, v133
	v_lshl_add_u32 v138, v11, 1, v0
	v_mov_b32_e32 v139, v133
	v_mov_b64_e32 v[140:141], 0x1d80
	v_mov_b64_e32 v[142:143], 0x1d7f
	v_add_u32_e32 v147, s75, v145
	v_add_u32_e32 v148, 0, v3
	v_add_u32_e32 v149, s76, v145
	s_movk_i32 s77, 0x7600
	s_barrier
	s_cmpk_le_u32 s33, 0xff
	s_cbranch_scc1 .Lp1prio_done
	s_setprio 1
.Lp1prio_done:
.LBB0_110:
	s_add_i32 s70, s70, 1
	s_mul_i32 s0, s70, s73
	s_mul_hi_u32 s1, s70, s74
	s_add_i32 s1, s1, s0
	s_mul_i32 s0, s70, s74
	s_add_u32 s48, s0, s6
	s_addc_u32 s49, s1, s59
	v_cmp_gt_i64_e64 s[2:3], s[48:49], v[142:143]
	s_and_b64 vcc, exec, s[2:3]
	s_cbranch_vccnz .LBB0_112
	s_ashr_i32 s0, s48, 31
	s_lshr_b32 s0, s0, 29
	s_add_i32 s0, s48, s0
	s_ashr_i32 s1, s0, 3
	s_and_b32 s0, s0, -8
	s_sub_i32 s0, s48, s0
	s_cmp_lt_i32 s0, 0
	s_cselect_b32 s16, s60, 0x3b0
	s_mul_i32 s0, s16, s0
	s_add_i32 s0, s0, s1
	s_mul_hi_i32 s1, s0, 0x22b63cbf
	s_lshr_b32 s16, s1, 31
	s_ashr_i32 s1, s1, 6
	s_add_i32 s1, s1, s16
	s_lshl_b32 s17, s1, 3
	s_sub_i32 s16, 0x80, s17
	s_min_i32 s46, s16, 8
	s_abs_i32 s16, s46
	v_cvt_f32_u32_e32 v0, s16
	s_sub_i32 s50, 0, s16
	s_mulk_i32 s1, 0x1d8
	s_sub_i32 s0, s0, s1
	v_rcp_iflag_f32_e32 v0, v0
	s_abs_i32 s1, s0
	s_xor_b32 s47, s0, s46
	s_ashr_i32 s47, s47, 31
	v_mul_f32_e32 v0, 0x4f7ffffe, v0
	v_cvt_u32_f32_e32 v0, v0
	s_nop 0
	v_readfirstlane_b32 s51, v0
	s_mul_i32 s50, s50, s51
	s_mul_hi_u32 s50, s51, s50
	s_add_i32 s51, s51, s50
	s_mul_hi_u32 s50, s1, s51
	s_mul_i32 s51, s50, s16
	s_sub_i32 s1, s1, s51
	s_add_i32 s56, s50, 1
	s_sub_i32 s51, s1, s16
	s_cmp_ge_u32 s1, s16
	s_cselect_b32 s50, s56, s50
	s_cselect_b32 s1, s51, s1
	s_add_i32 s51, s50, 1
	s_cmp_ge_u32 s1, s16
	s_cselect_b32 s1, s51, s50
	s_xor_b32 s1, s1, s47
	s_sub_i32 s16, s1, s47
	s_mul_i32 s1, s16, s46
	s_sub_i32 s0, s0, s1
	s_add_i32 s46, s0, s17
